# merge: next segment's k-tile 1 loaded at the start of the gating epilogue into free fragment/gate registers; first k-iteration of such a segment skips the vmcnt waits
# speedup vs baseline: 1.0021x; 1.0015x over previous
; #define RTID opaque_tid()
; #define ZERO_ACC(acc)                                  \
;   _Pragma("unroll") for (int i_ = 0; i_ < 4; ++i_)     \
;   _Pragma("unroll") for (int j_ = 0; j_ < 4; ++j_) { acc[i_][j_] = (f32x4){0.f, 0.f, 0.f, 0.f}; }
; template <int MI, int NJ> ...
;     ...
;   if (!pre) G8LOADP(Ag, Bg);
;   G8STORE(0);
;   {
;     const u16* ga_ = (1 < nk) ? Ag + 64 : Ag + nAoff;
;     const u16* gb_ = (1 < nk) ? Bg + 64 : Bg + nBoff;
;     G8LOADP(ga_, gb_);
;   }
;   __syncthreads();
;   const int sw0 = ((lane >> 4) ^ (lane & 7)) * 8;
;   const int dsw = (sw0 ^ 32) - sw0;
;   const u16* ra_ = sA + (wm * (16 * MI) + (lane & 15)) * 64 + sw0;
;   const u16* rb_ = sB + (wn * (16 * NJ) + (lane & 15)) * 64 + sw0;
; __device__ __forceinline__ void phase_merge(const Params& p, u16* smem, volatile LAS unsigned* vb_) {
;     ...
;     for (int n = 0; n < 3; ++n) {
;       f32x4 acc[4][4];
;       ZERO_ACC(acc);
;       gemm8<4, 4>(acc, G8REGS_ARGS, pre, Y, 1536, W, 1536, n * 512, n * 512 + 512, mt * 128, nt * 256,
;                   (n < 2) ? mt * 128 : nmt * 128, (n < 2) ? nt * 256 : nnt * 256, (n < 2) ? (n + 1) * 512 : 0, smem, tid);
;       pre = true;
;       const int tid2 = RTID;
; #pragma unroll
;       for (int k = 0; k < 8; ++k) {
;         const int c = tid2 + 512 * k;
;         const int row = c >> 5, ch = c & 31;
;         *(uint4*)(smem + row * 264 + ch * 8) = *(const uint4*)(MG + (size_t)(mt * 128 + row) * 3072 + n * 1024 + nt * 256 + ch * 8);
;       }
.LBB0_25:
	s_lshl_b32 s13, s39, 9
	s_waitcnt vmcnt(5)
	ds_write_b128 v183, v[2:5]
	s_waitcnt vmcnt(3)
	ds_write_b128 v183, v[10:13] offset:8192
	ds_write_b128 v183, v[6:9] offset:32768
	s_waitcnt vmcnt(2)
	ds_write_b128 v183, v[14:17] offset:40960
	s_waitcnt vmcnt(1)
	ds_write_b128 v183, v[18:21] offset:49152
	s_waitcnt vmcnt(0)
	ds_write_b128 v183, v[22:25] offset:57344
	v_add_co_u32_e32 v6, vcc, s77, v28
	s_add_i32 s40, s13, 0x200
	s_nop 0
	v_addc_co_u32_e32 v7, vcc, 0, v29, vcc
	s_cmp_eq_u32 s39, 2
	v_add_co_u32_e32 v14, vcc, s77, v26
	s_cselect_b32 s44, 0, s40
	s_nop 0
	v_addc_co_u32_e32 v15, vcc, 0, v27, vcc
	s_cselect_b32 s40, s23, 0
	s_cselect_b32 s46, s36, 0
	s_sub_i32 s44, s44, s13
	v_add_co_u32_e32 v18, vcc, 0x60000, v26
	s_ashr_i32 s41, s40, 31
	s_ashr_i32 s45, s44, 31
	v_addc_co_u32_e32 v19, vcc, 0, v27, vcc
	v_lshl_add_u64 v[2:3], s[40:41], 1, v[28:29]
	s_lshl_b64 s[40:41], s[44:45], 1
	v_mov_b32_e32 v0, 0xc00
	v_add_co_u32_e32 v22, vcc, 0x90000, v26
	v_lshl_add_u64 v[172:173], v[2:3], 0, s[40:41]
	v_mad_i64_i32 v[2:3], s[44:45], s46, v0, v[26:27]
	v_addc_co_u32_e32 v23, vcc, 0, v27, vcc
	v_lshl_add_u64 v[176:177], v[2:3], 0, s[40:41]
	s_cmp_lg_u32 s12, 0
	s_cbranch_scc1 .Lmg_pre
	global_load_dwordx4 v[2:5], v[28:29], off offset:128
	global_load_dwordx4 v[10:13], v[6:7], off offset:128
	s_nop 0
	global_load_dwordx4 v[6:9], v[26:27], off offset:128
	global_load_dwordx4 v[14:17], v[14:15], off offset:128
	global_load_dwordx4 v[18:21], v[18:19], off offset:128
	global_load_dwordx4 v[22:25], v[22:23], off offset:128
	s_mov_b32 s98, 0
	s_branch .Lmg_join
.Lmg_pre:
	s_mov_b32 s98, 1
	v_mov_b64_e32 v[2:3], v[188:189]
	v_mov_b64_e32 v[4:5], v[190:191]
	v_mov_b64_e32 v[10:11], v[192:193]
	v_mov_b64_e32 v[12:13], v[194:195]
	v_mov_b64_e32 v[6:7], v[196:197]
	v_mov_b64_e32 v[8:9], v[198:199]
	v_mov_b64_e32 v[14:15], v[246:247]
	v_mov_b64_e32 v[16:17], v[248:249]
	v_mov_b64_e32 v[18:19], v[234:235]
	v_mov_b64_e32 v[20:21], v[236:237]
	v_mov_b64_e32 v[22:23], v[238:239]
	v_mov_b64_e32 v[24:25], v[240:241]
.Lmg_join:
	v_mov_b32_e32 v26, 0
	s_mov_b32 s12, 0
	v_mov_b64_e32 v[178:179], v[132:133]
	v_mov_b64_e32 v[180:181], v[128:129]
	v_mov_b32_e32 v27, v26
	v_mov_b32_e32 v28, v26
	v_mov_b32_e32 v29, v26
	v_mov_b32_e32 v30, v26
	v_mov_b32_e32 v31, v26
	v_mov_b32_e32 v32, v26
	v_mov_b32_e32 v33, v26
	v_mov_b32_e32 v34, v26
	v_mov_b32_e32 v35, v26
	v_mov_b32_e32 v36, v26
	v_mov_b32_e32 v37, v26
	v_mov_b32_e32 v38, v26
	v_mov_b32_e32 v39, v26
	v_mov_b32_e32 v40, v26
	v_mov_b32_e32 v41, v26
	v_mov_b32_e32 v42, v26
	v_mov_b32_e32 v43, v26
	v_mov_b32_e32 v44, v26
	v_mov_b32_e32 v45, v26
	v_mov_b32_e32 v46, v26
	v_mov_b32_e32 v47, v26
	v_mov_b32_e32 v48, v26
	v_mov_b32_e32 v49, v26
	v_mov_b32_e32 v50, v26
	v_mov_b32_e32 v51, v26
	v_mov_b32_e32 v52, v26
	v_mov_b32_e32 v53, v26
	v_mov_b32_e32 v54, v26
	v_mov_b32_e32 v55, v26
	v_mov_b32_e32 v56, v26
	v_mov_b32_e32 v57, v26
	v_mov_b32_e32 v58, v26
	v_mov_b32_e32 v59, v26
	v_mov_b32_e32 v60, v26
	v_mov_b32_e32 v61, v26
	v_mov_b32_e32 v62, v26
	v_mov_b32_e32 v63, v26
	v_mov_b32_e32 v64, v26
	v_mov_b32_e32 v65, v26
	v_mov_b32_e32 v66, v26
	v_mov_b32_e32 v67, v26
	v_mov_b32_e32 v68, v26
	v_mov_b32_e32 v69, v26
	v_mov_b32_e32 v70, v26
	v_mov_b32_e32 v71, v26
	v_mov_b32_e32 v72, v26
	v_mov_b32_e32 v73, v26
	v_mov_b32_e32 v74, v26
	v_mov_b32_e32 v75, v26
	v_mov_b32_e32 v76, v26
	v_mov_b32_e32 v77, v26
	v_mov_b32_e32 v78, v26
	v_mov_b32_e32 v79, v26
	v_mov_b32_e32 v80, v26
	v_mov_b32_e32 v81, v26
	v_mov_b32_e32 v82, v26
	v_mov_b32_e32 v83, v26
	v_mov_b32_e32 v84, v26
	v_mov_b32_e32 v85, v26
	v_mov_b32_e32 v86, v26
	v_mov_b32_e32 v87, v26
	v_mov_b32_e32 v88, v26
	v_mov_b32_e32 v89, v26
	s_lshl_b32 s47, s39, 11
	s_add_u32 s48, s37, s47
	s_addc_u32 s49, s38, 0
	s_mul_i32 s47, s22, 0x1800
	s_add_u32 s48, s48, s47
	s_addc_u32 s49, s49, 0
	v_lshrrev_b32_e32 v250, 5, v175
	v_and_b32_e32 v251, 31, v175
	v_mul_u32_u24_e32 v250, 0x1800, v250
	v_lshl_add_u32 v250, v251, 4, v250
	global_load_dwordx4 v[212:215], v250, s[48:49]
	s_add_u32 s50, s48, 0x18000
	s_addc_u32 s51, s49, 0
	global_load_dwordx4 v[216:219], v250, s[50:51]
	s_add_u32 s52, s50, 0x18000
	s_addc_u32 s53, s51, 0
	global_load_dwordx4 v[220:223], v250, s[52:53]
	s_add_u32 s48, s52, 0x18000
	s_addc_u32 s49, s53, 0
	global_load_dwordx4 v[224:227], v250, s[48:49]
	s_add_u32 s50, s48, 0x18000
	s_addc_u32 s51, s49, 0
	global_load_dwordx4 v[234:237], v250, s[50:51]
	s_add_u32 s52, s50, 0x18000
	s_addc_u32 s53, s51, 0
	global_load_dwordx4 v[238:241], v250, s[52:53]
	s_add_u32 s48, s52, 0x18000
	s_addc_u32 s49, s53, 0
	global_load_dwordx4 v[242:245], v250, s[48:49]
	s_add_u32 s50, s48, 0x18000
	s_addc_u32 s51, s49, 0
	global_load_dwordx2 v[228:229], v250, s[50:51]
	global_load_dwordx2 v[250:251], v250, s[50:51] offset:8
	s_waitcnt lgkmcnt(0)
	s_barrier
.LBB0_26:
	s_and_b32 s13, s12, 1
	s_xor_b32 s40, s13, 1
	s_cmp_lt_u32 s12, 6
	v_lshl_add_u32 v0, s40, 14, v183
	s_cselect_b64 vcc, -1, 0
	v_lshl_add_u32 v187, s40, 15, v183
	s_cmp_eq_u32 s12, 0
	s_cselect_b32 s99, s98, 0
	s_cmp_lg_u32 s99, 0
	s_cbranch_scc1 .Lmg_nowait
	s_waitcnt vmcnt(5)
	ds_write_b128 v0, v[2:5]
	s_waitcnt vmcnt(3)
	ds_write_b128 v0, v[10:13] offset:8192
	s_waitcnt vmcnt(3)
	ds_write_b128 v187, v[6:9] offset:32768
	s_waitcnt vmcnt(2)
	ds_write_b128 v187, v[14:17] offset:40960
	s_waitcnt vmcnt(1)
	ds_write_b128 v187, v[18:21] offset:49152
	s_waitcnt vmcnt(0)
	ds_write_b128 v187, v[22:25] offset:57344
	s_branch .Lmg_wdone
.Lmg_nowait:
	ds_write_b128 v0, v[2:5]
	ds_write_b128 v0, v[10:13] offset:8192
	ds_write_b128 v187, v[6:9] offset:32768
	ds_write_b128 v187, v[14:17] offset:40960
	ds_write_b128 v187, v[18:21] offset:49152
	ds_write_b128 v187, v[22:25] offset:57344
; template <int MI, int NJ> ...
;     ...
;   for (int kt = 0; kt < nk; ++kt) {
;     const int buf = kt & 1;
;     {
;       G8STORE(buf ^ 1);
;       const u16* ga_ = (kt + 2 < nk) ? Ag + (kt + 2) * 64 : Ag + nAoff;
;       const u16* gb_ = (kt + 2 < nk) ? Bg + (kt + 2) * 64 : Bg + nBoff;
;       G8LOADP(ga_, gb_);
;     }
;     __builtin_amdgcn_sched_barrier(0);
;     __builtin_amdgcn_s_setprio(1);
;     const u16* a = ra_ + buf * AROWS * 64;
;     const u16* b = rb_ + buf * BROWS * 64;
; #pragma unroll
;     for (int ks = 0; ks < 2; ++ks) {
;       const u16* a_ = ks ? a + dsw : a;
;       const u16* b_ = ks ? b + dsw : b;
;       bf16x8 bfr[NJ];
; #pragma unroll
;       for (int j = 0; j < NJ; ++j) bfr[j] = *(const bf16x8*)(b_ + j * 16 * 64);
; #pragma unroll
;       for (int ih = 0; ih < MI / 4; ++ih) {
;         bf16x8 af[4];
; #pragma unroll
;         for (int i = 0; i < 4; ++i) af[i] = *(const bf16x8*)(a_ + (ih * 4 + i) * 16 * 64);
; #pragma unroll
;         for (int i = 0; i < 4; ++i)
; #pragma unroll
;           for (int j = 0; j < NJ; ++j) acc[ih * 4 + i][j] = mfma16(af[i], bfr[j], acc[ih * 4 + i][j]);
;       }
;     }
;     __builtin_amdgcn_s_setprio(0);
;     __builtin_amdgcn_sched_barrier(0);
;     __syncthreads();
;   }
; __device__ __forceinline__ void phase_merge(const Params& p, u16* smem, volatile LAS unsigned* vb_) {
;     ...
;       for (int k = 0; k < 8; ++k) {
;         const int c = tid2 + 512 * k;
;         const int row = c >> 5, ch = c & 31;
;         *(uint4*)(smem + row * 264 + ch * 8) = *(const uint4*)(MG + (size_t)(mt * 128 + row) * 3072 + n * 1024 + nt * 256 + ch * 8);
;       }
;       __syncthreads();
.Lmg_wdone:
	v_cndmask_b32_e32 v6, v172, v178, vcc
	v_cndmask_b32_e32 v7, v173, v179, vcc
	v_cndmask_b32_e32 v11, v177, v181, vcc
	v_cndmask_b32_e32 v10, v176, v180, vcc
	v_add_co_u32_e32 v12, vcc, s77, v6
	s_mov_b32 s40, 0x90000
	s_nop 0
	v_addc_co_u32_e32 v13, vcc, 0, v7, vcc
	v_add_co_u32_e32 v14, vcc, s77, v10
	global_load_dwordx4 v[2:5], v[6:7], off
	s_nop 0
	v_addc_co_u32_e32 v15, vcc, 0, v11, vcc
	v_add_co_u32_e32 v18, vcc, s54, v10
	global_load_dwordx4 v[6:9], v[10:11], off
	s_nop 0
	v_addc_co_u32_e32 v19, vcc, 0, v11, vcc
	v_add_co_u32_e32 v22, vcc, s40, v10
	s_nop 1
	v_addc_co_u32_e32 v23, vcc, 0, v11, vcc
	global_load_dwordx4 v[10:13], v[12:13], off
	s_nop 0
	global_load_dwordx4 v[14:17], v[14:15], off
	s_nop 0
	global_load_dwordx4 v[18:21], v[18:19], off
	s_nop 0
	global_load_dwordx4 v[22:25], v[22:23], off
	s_setprio 1
	v_lshl_add_u32 v0, s13, 14, v184
	v_lshl_or_b32 v187, s13, 15, v185
	ds_read_b128 v[192:195], v187 offset:32768
	ds_read_b128 v[196:199], v187 offset:34816
	ds_read_b128 v[204:207], v187 offset:36864
	ds_read_b128 v[208:211], v187 offset:38912
	ds_read_b128 v[188:191], v0
	ds_read_b128 v[246:249], v0 offset:2048
	v_add_u32_e32 v187, v187, v186
	s_waitcnt lgkmcnt(1)
	v_mfma_f32_16x16x32_bf16 v[86:89], v[188:191], v[192:195], v[86:89]
	s_waitcnt lgkmcnt(4)
	v_mfma_f32_16x16x32_bf16 v[82:85], v[188:191], v[196:199], v[82:85]
	s_waitcnt lgkmcnt(3)
	v_mfma_f32_16x16x32_bf16 v[78:81], v[188:191], v[204:207], v[78:81]
	s_waitcnt lgkmcnt(2)
	v_mfma_f32_16x16x32_bf16 v[74:77], v[188:191], v[208:211], v[74:77]
	ds_read_b128 v[188:191], v0 offset:4096
	s_waitcnt lgkmcnt(1)
	v_mfma_f32_16x16x32_bf16 v[70:73], v[246:249], v[192:195], v[70:73]
	v_mfma_f32_16x16x32_bf16 v[66:69], v[246:249], v[196:199], v[66:69]
	v_mfma_f32_16x16x32_bf16 v[62:65], v[246:249], v[204:207], v[62:65]
	v_mfma_f32_16x16x32_bf16 v[58:61], v[246:249], v[208:211], v[58:61]
	ds_read_b128 v[246:249], v0 offset:6144
	v_add_u32_e32 v0, v0, v186
	s_waitcnt lgkmcnt(1)
	v_mfma_f32_16x16x32_bf16 v[54:57], v[188:191], v[192:195], v[54:57]
	v_mfma_f32_16x16x32_bf16 v[50:53], v[188:191], v[196:199], v[50:53]
	v_mfma_f32_16x16x32_bf16 v[46:49], v[188:191], v[204:207], v[46:49]
	v_mfma_f32_16x16x32_bf16 v[42:45], v[188:191], v[208:211], v[42:45]
	ds_read_b128 v[188:191], v0
	s_waitcnt lgkmcnt(1)
	v_mfma_f32_16x16x32_bf16 v[38:41], v[246:249], v[192:195], v[38:41]
	ds_read_b128 v[192:195], v187 offset:32768
	v_mfma_f32_16x16x32_bf16 v[34:37], v[246:249], v[196:199], v[34:37]
	ds_read_b128 v[196:199], v187 offset:34816
	v_mfma_f32_16x16x32_bf16 v[30:33], v[246:249], v[204:207], v[30:33]
	ds_read_b128 v[204:207], v187 offset:36864
	v_mfma_f32_16x16x32_bf16 v[26:29], v[246:249], v[208:211], v[26:29]
	ds_read_b128 v[208:211], v187 offset:38912
	ds_read_b128 v[246:249], v0 offset:2048
	s_waitcnt lgkmcnt(4)
	v_mfma_f32_16x16x32_bf16 v[86:89], v[188:191], v[192:195], v[86:89]
	s_waitcnt lgkmcnt(3)
	v_mfma_f32_16x16x32_bf16 v[82:85], v[188:191], v[196:199], v[82:85]
	s_waitcnt lgkmcnt(2)
	v_mfma_f32_16x16x32_bf16 v[78:81], v[188:191], v[204:207], v[78:81]
	s_waitcnt lgkmcnt(1)
	v_mfma_f32_16x16x32_bf16 v[74:77], v[188:191], v[208:211], v[74:77]
	ds_read_b128 v[188:191], v0 offset:4096
	s_waitcnt lgkmcnt(1)
	v_mfma_f32_16x16x32_bf16 v[70:73], v[246:249], v[192:195], v[70:73]
	v_mfma_f32_16x16x32_bf16 v[66:69], v[246:249], v[196:199], v[66:69]
	v_mfma_f32_16x16x32_bf16 v[62:65], v[246:249], v[204:207], v[62:65]
	v_mfma_f32_16x16x32_bf16 v[58:61], v[246:249], v[208:211], v[58:61]
	ds_read_b128 v[246:249], v0 offset:6144
	s_waitcnt lgkmcnt(1)
	v_mfma_f32_16x16x32_bf16 v[54:57], v[188:191], v[192:195], v[54:57]
	v_mfma_f32_16x16x32_bf16 v[50:53], v[188:191], v[196:199], v[50:53]
	v_mfma_f32_16x16x32_bf16 v[46:49], v[188:191], v[204:207], v[46:49]
	v_mfma_f32_16x16x32_bf16 v[42:45], v[188:191], v[208:211], v[42:45]
	s_waitcnt lgkmcnt(0)
	v_mfma_f32_16x16x32_bf16 v[38:41], v[246:249], v[192:195], v[38:41]
	v_mfma_f32_16x16x32_bf16 v[34:37], v[246:249], v[196:199], v[34:37]
	v_mfma_f32_16x16x32_bf16 v[30:33], v[246:249], v[204:207], v[30:33]
	v_mfma_f32_16x16x32_bf16 v[26:29], v[246:249], v[208:211], v[26:29]
	s_setprio 0
	s_add_i32 s12, s12, 1
	v_lshl_add_u64 v[180:181], v[180:181], 0, s[26:27]
	s_cmp_lg_u32 s12, 8
	v_lshl_add_u64 v[178:179], v[178:179], 0, s[26:27]
	s_barrier
	s_cbranch_scc1 .LBB0_26
	v_lshrrev_b32_e32 v204, 5, v175
	v_and_b32_e32 v205, 31, v175
	v_mul_u32_u24_e32 v204, 0x210, v204
	v_lshl_add_u32 v204, v205, 4, v204
	s_waitcnt vmcnt(6)
	ds_write_b128 v204, v[212:215]
	ds_write_b128 v204, v[216:219] offset:8448
	ds_write_b128 v204, v[220:223] offset:16896
	ds_write_b128 v204, v[224:227] offset:25344
	ds_write_b128 v204, v[234:237] offset:33792
	ds_write_b128 v204, v[238:241] offset:42240
	ds_write_b128 v204, v[242:245] offset:50688
	ds_write_b64 v204, v[228:229] offset:59136
	ds_write_b64 v204, v[250:251] offset:59144
	global_load_dwordx4 v[188:191], v[172:173], off offset:128
	v_add_co_u32_e32 v192, vcc, s77, v172
	s_nop 1
	v_addc_co_u32_e32 v193, vcc, 0, v173, vcc
	global_load_dwordx4 v[192:195], v[192:193], off offset:128
	global_load_dwordx4 v[196:199], v[176:177], off offset:128
	v_add_co_u32_e32 v246, vcc, s77, v176
	s_nop 1
	v_addc_co_u32_e32 v247, vcc, 0, v177, vcc
	global_load_dwordx4 v[246:249], v[246:247], off offset:128
	v_add_co_u32_e32 v234, vcc, 0x60000, v176
	s_nop 1
	v_addc_co_u32_e32 v235, vcc, 0, v177, vcc
	global_load_dwordx4 v[234:237], v[234:235], off offset:128
	v_add_co_u32_e32 v238, vcc, 0x90000, v176
	s_nop 1
	v_addc_co_u32_e32 v239, vcc, 0, v177, vcc
	global_load_dwordx4 v[238:241], v[238:239], off offset:128
	s_waitcnt lgkmcnt(0)
	s_barrier
; __device__ __forceinline__ float bf2f(u16 h) { return __uint_as_float(((u32)h) << 16); }
; __device__ __forceinline__ float sigmoidf_(float x) { return 1.0f / (1.0f + __expf(-x)); }
; __device__ __forceinline__ void phase_merge(const Params& p, u16* smem, volatile LAS unsigned* vb_) {
;     ...
; #pragma unroll
;       for (int i = 0; i < 4; ++i)
; #pragma unroll
;         for (int j = 0; j < 4; ++j)
; #pragma unroll
;           for (int r = 0; r < 4; ++r) {
;             const float g = sigmoidf_(bf2f(smem[(wm * 64 + i * 16 + (lane >> 4) * 4 + r) * 264 + wn * 64 + j * 16 + (lane & 15)]));
;             tot[i][j][r] += g * acc[i][j][r];
;             if (r == 3) __builtin_amdgcn_sched_barrier(0);
;           }
	ds_read_u16 v212, v94
	ds_read_u16 v213, v94 offset:528
	ds_read_u16 v214, v94 offset:1056
	ds_read_u16 v215, v94 offset:1584
	ds_read_u16 v216, v94 offset:32
	ds_read_u16 v217, v94 offset:560
	ds_read_u16 v218, v94 offset:1088
	ds_read_u16 v219, v94 offset:1616
	s_waitcnt lgkmcnt(0)
	ds_read_u16 v204, v94 offset:64
	ds_read_u16 v205, v94 offset:592
	ds_read_u16 v206, v94 offset:1120
	ds_read_u16 v207, v94 offset:1648
	ds_read_u16 v208, v94 offset:96
	ds_read_u16 v209, v94 offset:624
	ds_read_u16 v210, v94 offset:1152
	ds_read_u16 v211, v94 offset:1680
	v_lshlrev_b32_e32 v212, 16, v212
	v_lshlrev_b32_e32 v213, 16, v213
	v_lshlrev_b32_e32 v214, 16, v214
	v_lshlrev_b32_e32 v215, 16, v215
	v_lshlrev_b32_e32 v216, 16, v216
	v_lshlrev_b32_e32 v217, 16, v217
	v_lshlrev_b32_e32 v218, 16, v218
	v_lshlrev_b32_e32 v219, 16, v219
	v_mul_f32_e32 v212, 0xbfb8aa3b, v212
	v_mul_f32_e32 v213, 0xbfb8aa3b, v213
	v_mul_f32_e32 v214, 0xbfb8aa3b, v214
	v_mul_f32_e32 v215, 0xbfb8aa3b, v215
	v_mul_f32_e32 v216, 0xbfb8aa3b, v216
	v_mul_f32_e32 v217, 0xbfb8aa3b, v217
	v_mul_f32_e32 v218, 0xbfb8aa3b, v218
	v_mul_f32_e32 v219, 0xbfb8aa3b, v219
	v_min_f32_e32 v212, 0x42fc0000, v212
	v_min_f32_e32 v213, 0x42fc0000, v213
	v_min_f32_e32 v214, 0x42fc0000, v214
	v_min_f32_e32 v215, 0x42fc0000, v215
	v_min_f32_e32 v216, 0x42fc0000, v216
	v_min_f32_e32 v217, 0x42fc0000, v217
	v_min_f32_e32 v218, 0x42fc0000, v218
	v_min_f32_e32 v219, 0x42fc0000, v219
	v_exp_f32_e32 v212, v212
	v_exp_f32_e32 v213, v213
	v_exp_f32_e32 v214, v214
	v_exp_f32_e32 v215, v215
	v_exp_f32_e32 v216, v216
	v_exp_f32_e32 v217, v217
	v_exp_f32_e32 v218, v218
	v_exp_f32_e32 v219, v219
	v_add_f32_e32 v212, 1.0, v212
	v_add_f32_e32 v213, 1.0, v213
	v_add_f32_e32 v214, 1.0, v214
	v_add_f32_e32 v215, 1.0, v215
	v_add_f32_e32 v216, 1.0, v216
	v_add_f32_e32 v217, 1.0, v217
	v_add_f32_e32 v218, 1.0, v218
	v_add_f32_e32 v219, 1.0, v219
	v_rcp_f32_e32 v220, v212
	v_rcp_f32_e32 v221, v213
	v_rcp_f32_e32 v222, v214
	v_rcp_f32_e32 v223, v215
	v_rcp_f32_e32 v224, v216
	v_rcp_f32_e32 v225, v217
	v_rcp_f32_e32 v226, v218
	v_rcp_f32_e32 v227, v219
	v_fma_f32 v212, -v212, v220, 1.0
	v_fma_f32 v213, -v213, v221, 1.0
	v_fma_f32 v214, -v214, v222, 1.0
	v_fma_f32 v215, -v215, v223, 1.0
	v_fma_f32 v216, -v216, v224, 1.0
	v_fma_f32 v217, -v217, v225, 1.0
	v_fma_f32 v218, -v218, v226, 1.0
	v_fma_f32 v219, -v219, v227, 1.0
	v_fmac_f32_e32 v220, v212, v220
	v_fmac_f32_e32 v221, v213, v221
	v_fmac_f32_e32 v222, v214, v222
	v_fmac_f32_e32 v223, v215, v223
	v_fmac_f32_e32 v224, v216, v224
	v_fmac_f32_e32 v225, v217, v225
	v_fmac_f32_e32 v226, v218, v226
	v_fmac_f32_e32 v227, v219, v227
	v_fmac_f32_e32 v170, v86, v220
	v_fmac_f32_e32 v171, v87, v221
	v_fmac_f32_e32 v168, v88, v222
	v_fmac_f32_e32 v169, v89, v223
	v_fmac_f32_e32 v166, v82, v224
	v_fmac_f32_e32 v167, v83, v225
	v_fmac_f32_e32 v164, v84, v226
	v_fmac_f32_e32 v165, v85, v227
	s_waitcnt lgkmcnt(0)
	ds_read_u16 v212, v94 offset:8448
	ds_read_u16 v213, v94 offset:8976
	ds_read_u16 v214, v94 offset:9504
	ds_read_u16 v215, v94 offset:10032
	ds_read_u16 v216, v94 offset:8480
	ds_read_u16 v217, v94 offset:9008
	ds_read_u16 v218, v94 offset:9536
	ds_read_u16 v219, v94 offset:10064
	v_lshlrev_b32_e32 v204, 16, v204
	v_lshlrev_b32_e32 v205, 16, v205
	v_lshlrev_b32_e32 v206, 16, v206
	v_lshlrev_b32_e32 v207, 16, v207
	v_lshlrev_b32_e32 v208, 16, v208
	v_lshlrev_b32_e32 v209, 16, v209
	v_lshlrev_b32_e32 v210, 16, v210
	v_lshlrev_b32_e32 v211, 16, v211
	v_mul_f32_e32 v204, 0xbfb8aa3b, v204
	v_mul_f32_e32 v205, 0xbfb8aa3b, v205
	v_mul_f32_e32 v206, 0xbfb8aa3b, v206
	v_mul_f32_e32 v207, 0xbfb8aa3b, v207
	v_mul_f32_e32 v208, 0xbfb8aa3b, v208
	v_mul_f32_e32 v209, 0xbfb8aa3b, v209
	v_mul_f32_e32 v210, 0xbfb8aa3b, v210
	v_mul_f32_e32 v211, 0xbfb8aa3b, v211
	v_min_f32_e32 v204, 0x42fc0000, v204
	v_min_f32_e32 v205, 0x42fc0000, v205
	v_min_f32_e32 v206, 0x42fc0000, v206
	v_min_f32_e32 v207, 0x42fc0000, v207
	v_min_f32_e32 v208, 0x42fc0000, v208
	v_min_f32_e32 v209, 0x42fc0000, v209
	v_min_f32_e32 v210, 0x42fc0000, v210
	v_min_f32_e32 v211, 0x42fc0000, v211
	v_exp_f32_e32 v204, v204
	v_exp_f32_e32 v205, v205
	v_exp_f32_e32 v206, v206
	v_exp_f32_e32 v207, v207
	v_exp_f32_e32 v208, v208
	v_exp_f32_e32 v209, v209
	v_exp_f32_e32 v210, v210
	v_exp_f32_e32 v211, v211
	v_add_f32_e32 v204, 1.0, v204
	v_add_f32_e32 v205, 1.0, v205
	v_add_f32_e32 v206, 1.0, v206
	v_add_f32_e32 v207, 1.0, v207
	v_add_f32_e32 v208, 1.0, v208
	v_add_f32_e32 v209, 1.0, v209
	v_add_f32_e32 v210, 1.0, v210
	v_add_f32_e32 v211, 1.0, v211
	v_rcp_f32_e32 v220, v204
	v_rcp_f32_e32 v221, v205
	v_rcp_f32_e32 v222, v206
	v_rcp_f32_e32 v223, v207
	v_rcp_f32_e32 v224, v208
	v_rcp_f32_e32 v225, v209
	v_rcp_f32_e32 v226, v210
	v_rcp_f32_e32 v227, v211
	v_fma_f32 v204, -v204, v220, 1.0
	v_fma_f32 v205, -v205, v221, 1.0
	v_fma_f32 v206, -v206, v222, 1.0
	v_fma_f32 v207, -v207, v223, 1.0
	v_fma_f32 v208, -v208, v224, 1.0
	v_fma_f32 v209, -v209, v225, 1.0
	v_fma_f32 v210, -v210, v226, 1.0
	v_fma_f32 v211, -v211, v227, 1.0
	v_fmac_f32_e32 v220, v204, v220
	v_fmac_f32_e32 v221, v205, v221
	v_fmac_f32_e32 v222, v206, v222
	v_fmac_f32_e32 v223, v207, v223
	v_fmac_f32_e32 v224, v208, v224
	v_fmac_f32_e32 v225, v209, v225
	v_fmac_f32_e32 v226, v210, v226
	v_fmac_f32_e32 v227, v211, v227
	v_fmac_f32_e32 v162, v78, v220
	v_fmac_f32_e32 v163, v79, v221
	v_fmac_f32_e32 v160, v80, v222
	v_fmac_f32_e32 v161, v81, v223
	v_fmac_f32_e32 v158, v74, v224
	v_fmac_f32_e32 v159, v75, v225
	v_fmac_f32_e32 v156, v76, v226
	v_fmac_f32_e32 v157, v77, v227
	s_waitcnt lgkmcnt(0)
; __device__ __forceinline__ float bf2f(u16 h) { return __uint_as_float(((u32)h) << 16); }
; __device__ __forceinline__ float sigmoidf_(float x) { return 1.0f / (1.0f + __expf(-x)); }
; __device__ __forceinline__ void phase_merge(const Params& p, u16* smem, volatile LAS unsigned* vb_) {
;     ...
; #pragma unroll
;       for (int i = 0; i < 4; ++i)
; #pragma unroll
;         for (int j = 0; j < 4; ++j)
; #pragma unroll
;           for (int r = 0; r < 4; ++r) {
;             const float g = sigmoidf_(bf2f(smem[(wm * 64 + i * 16 + (lane >> 4) * 4 + r) * 264 + wn * 64 + j * 16 + (lane & 15)]));
;             tot[i][j][r] += g * acc[i][j][r];
;             if (r == 3) __builtin_amdgcn_sched_barrier(0);
;           }
	ds_read_u16 v204, v94 offset:8512
	ds_read_u16 v205, v94 offset:9040
	ds_read_u16 v206, v94 offset:9568
	ds_read_u16 v207, v94 offset:10096
	ds_read_u16 v208, v94 offset:8544
	ds_read_u16 v209, v94 offset:9072
	ds_read_u16 v210, v94 offset:9600
	ds_read_u16 v211, v94 offset:10128
	v_lshlrev_b32_e32 v212, 16, v212
	v_lshlrev_b32_e32 v213, 16, v213
	v_lshlrev_b32_e32 v214, 16, v214
	v_lshlrev_b32_e32 v215, 16, v215
	v_lshlrev_b32_e32 v216, 16, v216
	v_lshlrev_b32_e32 v217, 16, v217
	v_lshlrev_b32_e32 v218, 16, v218
	v_lshlrev_b32_e32 v219, 16, v219
	v_mul_f32_e32 v212, 0xbfb8aa3b, v212
	v_mul_f32_e32 v213, 0xbfb8aa3b, v213
	v_mul_f32_e32 v214, 0xbfb8aa3b, v214
	v_mul_f32_e32 v215, 0xbfb8aa3b, v215
	v_mul_f32_e32 v216, 0xbfb8aa3b, v216
	v_mul_f32_e32 v217, 0xbfb8aa3b, v217
	v_mul_f32_e32 v218, 0xbfb8aa3b, v218
	v_mul_f32_e32 v219, 0xbfb8aa3b, v219
	v_min_f32_e32 v212, 0x42fc0000, v212
	v_min_f32_e32 v213, 0x42fc0000, v213
	v_min_f32_e32 v214, 0x42fc0000, v214
	v_min_f32_e32 v215, 0x42fc0000, v215
	v_min_f32_e32 v216, 0x42fc0000, v216
	v_min_f32_e32 v217, 0x42fc0000, v217
	v_min_f32_e32 v218, 0x42fc0000, v218
	v_min_f32_e32 v219, 0x42fc0000, v219
	v_exp_f32_e32 v212, v212
	v_exp_f32_e32 v213, v213
	v_exp_f32_e32 v214, v214
	v_exp_f32_e32 v215, v215
	v_exp_f32_e32 v216, v216
	v_exp_f32_e32 v217, v217
	v_exp_f32_e32 v218, v218
	v_exp_f32_e32 v219, v219
	v_add_f32_e32 v212, 1.0, v212
	v_add_f32_e32 v213, 1.0, v213
	v_add_f32_e32 v214, 1.0, v214
	v_add_f32_e32 v215, 1.0, v215
	v_add_f32_e32 v216, 1.0, v216
	v_add_f32_e32 v217, 1.0, v217
	v_add_f32_e32 v218, 1.0, v218
	v_add_f32_e32 v219, 1.0, v219
	v_rcp_f32_e32 v220, v212
	v_rcp_f32_e32 v221, v213
	v_rcp_f32_e32 v222, v214
	v_rcp_f32_e32 v223, v215
	v_rcp_f32_e32 v224, v216
	v_rcp_f32_e32 v225, v217
	v_rcp_f32_e32 v226, v218
	v_rcp_f32_e32 v227, v219
	v_fma_f32 v212, -v212, v220, 1.0
	v_fma_f32 v213, -v213, v221, 1.0
	v_fma_f32 v214, -v214, v222, 1.0
	v_fma_f32 v215, -v215, v223, 1.0
	v_fma_f32 v216, -v216, v224, 1.0
	v_fma_f32 v217, -v217, v225, 1.0
	v_fma_f32 v218, -v218, v226, 1.0
	v_fma_f32 v219, -v219, v227, 1.0
	v_fmac_f32_e32 v220, v212, v220
	v_fmac_f32_e32 v221, v213, v221
	v_fmac_f32_e32 v222, v214, v222
	v_fmac_f32_e32 v223, v215, v223
	v_fmac_f32_e32 v224, v216, v224
	v_fmac_f32_e32 v225, v217, v225
	v_fmac_f32_e32 v226, v218, v226
	v_fmac_f32_e32 v227, v219, v227
	v_fmac_f32_e32 v154, v70, v220
	v_fmac_f32_e32 v155, v71, v221
	v_fmac_f32_e32 v152, v72, v222
	v_fmac_f32_e32 v153, v73, v223
	v_fmac_f32_e32 v150, v66, v224
	v_fmac_f32_e32 v151, v67, v225
	v_fmac_f32_e32 v148, v68, v226
	v_fmac_f32_e32 v149, v69, v227
	s_waitcnt lgkmcnt(0)
	ds_read_u16 v212, v94 offset:16896
	ds_read_u16 v213, v94 offset:17424
	ds_read_u16 v214, v94 offset:17952
	ds_read_u16 v215, v94 offset:18480
	ds_read_u16 v216, v94 offset:16928
	ds_read_u16 v217, v94 offset:17456
	ds_read_u16 v218, v94 offset:17984
	ds_read_u16 v219, v94 offset:18512
	v_lshlrev_b32_e32 v204, 16, v204
	v_lshlrev_b32_e32 v205, 16, v205
	v_lshlrev_b32_e32 v206, 16, v206
	v_lshlrev_b32_e32 v207, 16, v207
	v_lshlrev_b32_e32 v208, 16, v208
	v_lshlrev_b32_e32 v209, 16, v209
	v_lshlrev_b32_e32 v210, 16, v210
	v_lshlrev_b32_e32 v211, 16, v211
	v_mul_f32_e32 v204, 0xbfb8aa3b, v204
	v_mul_f32_e32 v205, 0xbfb8aa3b, v205
	v_mul_f32_e32 v206, 0xbfb8aa3b, v206
	v_mul_f32_e32 v207, 0xbfb8aa3b, v207
	v_mul_f32_e32 v208, 0xbfb8aa3b, v208
	v_mul_f32_e32 v209, 0xbfb8aa3b, v209
	v_mul_f32_e32 v210, 0xbfb8aa3b, v210
	v_mul_f32_e32 v211, 0xbfb8aa3b, v211
	v_min_f32_e32 v204, 0x42fc0000, v204
	v_min_f32_e32 v205, 0x42fc0000, v205
	v_min_f32_e32 v206, 0x42fc0000, v206
	v_min_f32_e32 v207, 0x42fc0000, v207
	v_min_f32_e32 v208, 0x42fc0000, v208
	v_min_f32_e32 v209, 0x42fc0000, v209
	v_min_f32_e32 v210, 0x42fc0000, v210
	v_min_f32_e32 v211, 0x42fc0000, v211
	v_exp_f32_e32 v204, v204
	v_exp_f32_e32 v205, v205
	v_exp_f32_e32 v206, v206
	v_exp_f32_e32 v207, v207
	v_exp_f32_e32 v208, v208
	v_exp_f32_e32 v209, v209
	v_exp_f32_e32 v210, v210
	v_exp_f32_e32 v211, v211
	v_add_f32_e32 v204, 1.0, v204
	v_add_f32_e32 v205, 1.0, v205
	v_add_f32_e32 v206, 1.0, v206
	v_add_f32_e32 v207, 1.0, v207
	v_add_f32_e32 v208, 1.0, v208
	v_add_f32_e32 v209, 1.0, v209
	v_add_f32_e32 v210, 1.0, v210
	v_add_f32_e32 v211, 1.0, v211
	v_rcp_f32_e32 v220, v204
	v_rcp_f32_e32 v221, v205
	v_rcp_f32_e32 v222, v206
	v_rcp_f32_e32 v223, v207
	v_rcp_f32_e32 v224, v208
	v_rcp_f32_e32 v225, v209
	v_rcp_f32_e32 v226, v210
	v_rcp_f32_e32 v227, v211
	v_fma_f32 v204, -v204, v220, 1.0
	v_fma_f32 v205, -v205, v221, 1.0
	v_fma_f32 v206, -v206, v222, 1.0
	v_fma_f32 v207, -v207, v223, 1.0
	v_fma_f32 v208, -v208, v224, 1.0
	v_fma_f32 v209, -v209, v225, 1.0
	v_fma_f32 v210, -v210, v226, 1.0
	v_fma_f32 v211, -v211, v227, 1.0
	v_fmac_f32_e32 v220, v204, v220
	v_fmac_f32_e32 v221, v205, v221
	v_fmac_f32_e32 v222, v206, v222
	v_fmac_f32_e32 v223, v207, v223
	v_fmac_f32_e32 v224, v208, v224
	v_fmac_f32_e32 v225, v209, v225
	v_fmac_f32_e32 v226, v210, v226
	v_fmac_f32_e32 v227, v211, v227
	v_fmac_f32_e32 v146, v62, v220
	v_fmac_f32_e32 v147, v63, v221
	v_fmac_f32_e32 v144, v64, v222
	v_fmac_f32_e32 v145, v65, v223
	v_fmac_f32_e32 v138, v58, v224
	v_fmac_f32_e32 v139, v59, v225
	v_fmac_f32_e32 v136, v60, v226
	v_fmac_f32_e32 v137, v61, v227
	s_waitcnt lgkmcnt(0)
; __device__ __forceinline__ float bf2f(u16 h) { return __uint_as_float(((u32)h) << 16); }
; __device__ __forceinline__ float sigmoidf_(float x) { return 1.0f / (1.0f + __expf(-x)); }
; __device__ __forceinline__ void phase_merge(const Params& p, u16* smem, volatile LAS unsigned* vb_) {
;     ...
; #pragma unroll
;       for (int i = 0; i < 4; ++i)
; #pragma unroll
;         for (int j = 0; j < 4; ++j)
; #pragma unroll
;           for (int r = 0; r < 4; ++r) {
;             const float g = sigmoidf_(bf2f(smem[(wm * 64 + i * 16 + (lane >> 4) * 4 + r) * 264 + wn * 64 + j * 16 + (lane & 15)]));
;             tot[i][j][r] += g * acc[i][j][r];
;             if (r == 3) __builtin_amdgcn_sched_barrier(0);
;           }
	ds_read_u16 v204, v94 offset:16960
	ds_read_u16 v205, v94 offset:17488
	ds_read_u16 v206, v94 offset:18016
	ds_read_u16 v207, v94 offset:18544
	ds_read_u16 v208, v94 offset:16992
	ds_read_u16 v209, v94 offset:17520
	ds_read_u16 v210, v94 offset:18048
	ds_read_u16 v211, v94 offset:18576
	v_lshlrev_b32_e32 v212, 16, v212
	v_lshlrev_b32_e32 v213, 16, v213
	v_lshlrev_b32_e32 v214, 16, v214
	v_lshlrev_b32_e32 v215, 16, v215
	v_lshlrev_b32_e32 v216, 16, v216
	v_lshlrev_b32_e32 v217, 16, v217
	v_lshlrev_b32_e32 v218, 16, v218
	v_lshlrev_b32_e32 v219, 16, v219
	v_mul_f32_e32 v212, 0xbfb8aa3b, v212
	v_mul_f32_e32 v213, 0xbfb8aa3b, v213
	v_mul_f32_e32 v214, 0xbfb8aa3b, v214
	v_mul_f32_e32 v215, 0xbfb8aa3b, v215
	v_mul_f32_e32 v216, 0xbfb8aa3b, v216
	v_mul_f32_e32 v217, 0xbfb8aa3b, v217
	v_mul_f32_e32 v218, 0xbfb8aa3b, v218
	v_mul_f32_e32 v219, 0xbfb8aa3b, v219
	v_min_f32_e32 v212, 0x42fc0000, v212
	v_min_f32_e32 v213, 0x42fc0000, v213
	v_min_f32_e32 v214, 0x42fc0000, v214
	v_min_f32_e32 v215, 0x42fc0000, v215
	v_min_f32_e32 v216, 0x42fc0000, v216
	v_min_f32_e32 v217, 0x42fc0000, v217
	v_min_f32_e32 v218, 0x42fc0000, v218
	v_min_f32_e32 v219, 0x42fc0000, v219
	v_exp_f32_e32 v212, v212
	v_exp_f32_e32 v213, v213
	v_exp_f32_e32 v214, v214
	v_exp_f32_e32 v215, v215
	v_exp_f32_e32 v216, v216
	v_exp_f32_e32 v217, v217
	v_exp_f32_e32 v218, v218
	v_exp_f32_e32 v219, v219
	v_add_f32_e32 v212, 1.0, v212
	v_add_f32_e32 v213, 1.0, v213
	v_add_f32_e32 v214, 1.0, v214
	v_add_f32_e32 v215, 1.0, v215
	v_add_f32_e32 v216, 1.0, v216
	v_add_f32_e32 v217, 1.0, v217
	v_add_f32_e32 v218, 1.0, v218
	v_add_f32_e32 v219, 1.0, v219
	v_rcp_f32_e32 v220, v212
	v_rcp_f32_e32 v221, v213
	v_rcp_f32_e32 v222, v214
	v_rcp_f32_e32 v223, v215
	v_rcp_f32_e32 v224, v216
	v_rcp_f32_e32 v225, v217
	v_rcp_f32_e32 v226, v218
	v_rcp_f32_e32 v227, v219
	v_fma_f32 v212, -v212, v220, 1.0
	v_fma_f32 v213, -v213, v221, 1.0
	v_fma_f32 v214, -v214, v222, 1.0
	v_fma_f32 v215, -v215, v223, 1.0
	v_fma_f32 v216, -v216, v224, 1.0
	v_fma_f32 v217, -v217, v225, 1.0
	v_fma_f32 v218, -v218, v226, 1.0
	v_fma_f32 v219, -v219, v227, 1.0
	v_fmac_f32_e32 v220, v212, v220
	v_fmac_f32_e32 v221, v213, v221
	v_fmac_f32_e32 v222, v214, v222
	v_fmac_f32_e32 v223, v215, v223
	v_fmac_f32_e32 v224, v216, v224
	v_fmac_f32_e32 v225, v217, v225
	v_fmac_f32_e32 v226, v218, v226
	v_fmac_f32_e32 v227, v219, v227
	v_fmac_f32_e32 v134, v54, v220
	v_fmac_f32_e32 v135, v55, v221
	v_fmac_f32_e32 v130, v56, v222
	v_fmac_f32_e32 v131, v57, v223
	v_fmac_f32_e32 v126, v50, v224
	v_fmac_f32_e32 v127, v51, v225
	v_fmac_f32_e32 v124, v52, v226
	v_fmac_f32_e32 v125, v53, v227
	s_waitcnt lgkmcnt(0)
	ds_read_u16 v212, v94 offset:25344
	ds_read_u16 v213, v94 offset:25872
	ds_read_u16 v214, v94 offset:26400
	ds_read_u16 v215, v94 offset:26928
	ds_read_u16 v216, v94 offset:25376
	ds_read_u16 v217, v94 offset:25904
	ds_read_u16 v218, v94 offset:26432
	ds_read_u16 v219, v94 offset:26960
	v_lshlrev_b32_e32 v204, 16, v204
	v_lshlrev_b32_e32 v205, 16, v205
	v_lshlrev_b32_e32 v206, 16, v206
	v_lshlrev_b32_e32 v207, 16, v207
	v_lshlrev_b32_e32 v208, 16, v208
	v_lshlrev_b32_e32 v209, 16, v209
	v_lshlrev_b32_e32 v210, 16, v210
	v_lshlrev_b32_e32 v211, 16, v211
	v_mul_f32_e32 v204, 0xbfb8aa3b, v204
	v_mul_f32_e32 v205, 0xbfb8aa3b, v205
	v_mul_f32_e32 v206, 0xbfb8aa3b, v206
	v_mul_f32_e32 v207, 0xbfb8aa3b, v207
	v_mul_f32_e32 v208, 0xbfb8aa3b, v208
	v_mul_f32_e32 v209, 0xbfb8aa3b, v209
	v_mul_f32_e32 v210, 0xbfb8aa3b, v210
	v_mul_f32_e32 v211, 0xbfb8aa3b, v211
	v_min_f32_e32 v204, 0x42fc0000, v204
	v_min_f32_e32 v205, 0x42fc0000, v205
	v_min_f32_e32 v206, 0x42fc0000, v206
	v_min_f32_e32 v207, 0x42fc0000, v207
	v_min_f32_e32 v208, 0x42fc0000, v208
	v_min_f32_e32 v209, 0x42fc0000, v209
	v_min_f32_e32 v210, 0x42fc0000, v210
	v_min_f32_e32 v211, 0x42fc0000, v211
	v_exp_f32_e32 v204, v204
	v_exp_f32_e32 v205, v205
	v_exp_f32_e32 v206, v206
	v_exp_f32_e32 v207, v207
	v_exp_f32_e32 v208, v208
	v_exp_f32_e32 v209, v209
	v_exp_f32_e32 v210, v210
	v_exp_f32_e32 v211, v211
	v_add_f32_e32 v204, 1.0, v204
	v_add_f32_e32 v205, 1.0, v205
	v_add_f32_e32 v206, 1.0, v206
	v_add_f32_e32 v207, 1.0, v207
	v_add_f32_e32 v208, 1.0, v208
	v_add_f32_e32 v209, 1.0, v209
	v_add_f32_e32 v210, 1.0, v210
	v_add_f32_e32 v211, 1.0, v211
	v_rcp_f32_e32 v220, v204
	v_rcp_f32_e32 v221, v205
	v_rcp_f32_e32 v222, v206
	v_rcp_f32_e32 v223, v207
	v_rcp_f32_e32 v224, v208
	v_rcp_f32_e32 v225, v209
	v_rcp_f32_e32 v226, v210
	v_rcp_f32_e32 v227, v211
	v_fma_f32 v204, -v204, v220, 1.0
	v_fma_f32 v205, -v205, v221, 1.0
	v_fma_f32 v206, -v206, v222, 1.0
	v_fma_f32 v207, -v207, v223, 1.0
	v_fma_f32 v208, -v208, v224, 1.0
	v_fma_f32 v209, -v209, v225, 1.0
	v_fma_f32 v210, -v210, v226, 1.0
	v_fma_f32 v211, -v211, v227, 1.0
	v_fmac_f32_e32 v220, v204, v220
	v_fmac_f32_e32 v221, v205, v221
	v_fmac_f32_e32 v222, v206, v222
	v_fmac_f32_e32 v223, v207, v223
	v_fmac_f32_e32 v224, v208, v224
	v_fmac_f32_e32 v225, v209, v225
	v_fmac_f32_e32 v226, v210, v226
	v_fmac_f32_e32 v227, v211, v227
	v_fmac_f32_e32 v122, v46, v220
	v_fmac_f32_e32 v123, v47, v221
	v_fmac_f32_e32 v120, v48, v222
	v_fmac_f32_e32 v121, v49, v223
	v_fmac_f32_e32 v118, v42, v224
	v_fmac_f32_e32 v119, v43, v225
	v_fmac_f32_e32 v116, v44, v226
	v_fmac_f32_e32 v117, v45, v227
	s_waitcnt lgkmcnt(0)
; __device__ __forceinline__ float bf2f(u16 h) { return __uint_as_float(((u32)h) << 16); }
; __device__ __forceinline__ float sigmoidf_(float x) { return 1.0f / (1.0f + __expf(-x)); }
; __device__ __forceinline__ void phase_merge(const Params& p, u16* smem, volatile LAS unsigned* vb_) {
;     ...
; #pragma unroll
;       for (int i = 0; i < 4; ++i)
; #pragma unroll
;         for (int j = 0; j < 4; ++j)
; #pragma unroll
;           for (int r = 0; r < 4; ++r) {
;             const float g = sigmoidf_(bf2f(smem[(wm * 64 + i * 16 + (lane >> 4) * 4 + r) * 264 + wn * 64 + j * 16 + (lane & 15)]));
;             tot[i][j][r] += g * acc[i][j][r];
;             if (r == 3) __builtin_amdgcn_sched_barrier(0);
;           }
;       __syncthreads();
;     }
	ds_read_u16 v204, v94 offset:25408
	ds_read_u16 v205, v94 offset:25936
	ds_read_u16 v206, v94 offset:26464
	ds_read_u16 v207, v94 offset:26992
	ds_read_u16 v208, v94 offset:25440
	ds_read_u16 v209, v94 offset:25968
	ds_read_u16 v210, v94 offset:26496
	ds_read_u16 v211, v94 offset:27024
	v_lshlrev_b32_e32 v212, 16, v212
	v_lshlrev_b32_e32 v213, 16, v213
	v_lshlrev_b32_e32 v214, 16, v214
	v_lshlrev_b32_e32 v215, 16, v215
	v_lshlrev_b32_e32 v216, 16, v216
	v_lshlrev_b32_e32 v217, 16, v217
	v_lshlrev_b32_e32 v218, 16, v218
	v_lshlrev_b32_e32 v219, 16, v219
	v_mul_f32_e32 v212, 0xbfb8aa3b, v212
	v_mul_f32_e32 v213, 0xbfb8aa3b, v213
	v_mul_f32_e32 v214, 0xbfb8aa3b, v214
	v_mul_f32_e32 v215, 0xbfb8aa3b, v215
	v_mul_f32_e32 v216, 0xbfb8aa3b, v216
	v_mul_f32_e32 v217, 0xbfb8aa3b, v217
	v_mul_f32_e32 v218, 0xbfb8aa3b, v218
	v_mul_f32_e32 v219, 0xbfb8aa3b, v219
	v_min_f32_e32 v212, 0x42fc0000, v212
	v_min_f32_e32 v213, 0x42fc0000, v213
	v_min_f32_e32 v214, 0x42fc0000, v214
	v_min_f32_e32 v215, 0x42fc0000, v215
	v_min_f32_e32 v216, 0x42fc0000, v216
	v_min_f32_e32 v217, 0x42fc0000, v217
	v_min_f32_e32 v218, 0x42fc0000, v218
	v_min_f32_e32 v219, 0x42fc0000, v219
	v_exp_f32_e32 v212, v212
	v_exp_f32_e32 v213, v213
	v_exp_f32_e32 v214, v214
	v_exp_f32_e32 v215, v215
	v_exp_f32_e32 v216, v216
	v_exp_f32_e32 v217, v217
	v_exp_f32_e32 v218, v218
	v_exp_f32_e32 v219, v219
	v_add_f32_e32 v212, 1.0, v212
	v_add_f32_e32 v213, 1.0, v213
	v_add_f32_e32 v214, 1.0, v214
	v_add_f32_e32 v215, 1.0, v215
	v_add_f32_e32 v216, 1.0, v216
	v_add_f32_e32 v217, 1.0, v217
	v_add_f32_e32 v218, 1.0, v218
	v_add_f32_e32 v219, 1.0, v219
	v_rcp_f32_e32 v220, v212
	v_rcp_f32_e32 v221, v213
	v_rcp_f32_e32 v222, v214
	v_rcp_f32_e32 v223, v215
	v_rcp_f32_e32 v224, v216
	v_rcp_f32_e32 v225, v217
	v_rcp_f32_e32 v226, v218
	v_rcp_f32_e32 v227, v219
	v_fma_f32 v212, -v212, v220, 1.0
	v_fma_f32 v213, -v213, v221, 1.0
	v_fma_f32 v214, -v214, v222, 1.0
	v_fma_f32 v215, -v215, v223, 1.0
	v_fma_f32 v216, -v216, v224, 1.0
	v_fma_f32 v217, -v217, v225, 1.0
	v_fma_f32 v218, -v218, v226, 1.0
	v_fma_f32 v219, -v219, v227, 1.0
	v_fmac_f32_e32 v220, v212, v220
	v_fmac_f32_e32 v221, v213, v221
	v_fmac_f32_e32 v222, v214, v222
	v_fmac_f32_e32 v223, v215, v223
	v_fmac_f32_e32 v224, v216, v224
	v_fmac_f32_e32 v225, v217, v225
	v_fmac_f32_e32 v226, v218, v226
	v_fmac_f32_e32 v227, v219, v227
	v_fmac_f32_e32 v114, v38, v220
	v_fmac_f32_e32 v115, v39, v221
	v_fmac_f32_e32 v112, v40, v222
	v_fmac_f32_e32 v113, v41, v223
	v_fmac_f32_e32 v110, v34, v224
	v_fmac_f32_e32 v111, v35, v225
	v_fmac_f32_e32 v108, v36, v226
	v_fmac_f32_e32 v109, v37, v227
	s_waitcnt lgkmcnt(0)
	v_lshlrev_b32_e32 v204, 16, v204
	v_lshlrev_b32_e32 v205, 16, v205
	v_lshlrev_b32_e32 v206, 16, v206
	v_lshlrev_b32_e32 v207, 16, v207
	v_lshlrev_b32_e32 v208, 16, v208
	v_lshlrev_b32_e32 v209, 16, v209
	v_lshlrev_b32_e32 v210, 16, v210
	v_lshlrev_b32_e32 v211, 16, v211
	v_mul_f32_e32 v204, 0xbfb8aa3b, v204
	v_mul_f32_e32 v205, 0xbfb8aa3b, v205
	v_mul_f32_e32 v206, 0xbfb8aa3b, v206
	v_mul_f32_e32 v207, 0xbfb8aa3b, v207
	v_mul_f32_e32 v208, 0xbfb8aa3b, v208
	v_mul_f32_e32 v209, 0xbfb8aa3b, v209
	v_mul_f32_e32 v210, 0xbfb8aa3b, v210
	v_mul_f32_e32 v211, 0xbfb8aa3b, v211
	v_min_f32_e32 v204, 0x42fc0000, v204
	v_min_f32_e32 v205, 0x42fc0000, v205
	v_min_f32_e32 v206, 0x42fc0000, v206
	v_min_f32_e32 v207, 0x42fc0000, v207
	v_min_f32_e32 v208, 0x42fc0000, v208
	v_min_f32_e32 v209, 0x42fc0000, v209
	v_min_f32_e32 v210, 0x42fc0000, v210
	v_min_f32_e32 v211, 0x42fc0000, v211
	v_exp_f32_e32 v204, v204
	v_exp_f32_e32 v205, v205
	v_exp_f32_e32 v206, v206
	v_exp_f32_e32 v207, v207
	v_exp_f32_e32 v208, v208
	v_exp_f32_e32 v209, v209
	v_exp_f32_e32 v210, v210
	v_exp_f32_e32 v211, v211
	v_add_f32_e32 v204, 1.0, v204
	v_add_f32_e32 v205, 1.0, v205
	v_add_f32_e32 v206, 1.0, v206
	v_add_f32_e32 v207, 1.0, v207
	v_add_f32_e32 v208, 1.0, v208
	v_add_f32_e32 v209, 1.0, v209
	v_add_f32_e32 v210, 1.0, v210
	v_add_f32_e32 v211, 1.0, v211
	v_rcp_f32_e32 v220, v204
	v_rcp_f32_e32 v221, v205
	v_rcp_f32_e32 v222, v206
	v_rcp_f32_e32 v223, v207
	v_rcp_f32_e32 v224, v208
	v_rcp_f32_e32 v225, v209
	v_rcp_f32_e32 v226, v210
	v_rcp_f32_e32 v227, v211
	v_fma_f32 v204, -v204, v220, 1.0
	v_fma_f32 v205, -v205, v221, 1.0
	v_fma_f32 v206, -v206, v222, 1.0
	v_fma_f32 v207, -v207, v223, 1.0
	v_fma_f32 v208, -v208, v224, 1.0
	v_fma_f32 v209, -v209, v225, 1.0
	v_fma_f32 v210, -v210, v226, 1.0
	v_fma_f32 v211, -v211, v227, 1.0
	v_fmac_f32_e32 v220, v204, v220
	v_fmac_f32_e32 v221, v205, v221
	v_fmac_f32_e32 v222, v206, v222
	v_fmac_f32_e32 v223, v207, v223
	v_fmac_f32_e32 v224, v208, v224
	v_fmac_f32_e32 v225, v209, v225
	v_fmac_f32_e32 v226, v210, v226
	v_fmac_f32_e32 v227, v211, v227
	v_fmac_f32_e32 v106, v30, v220
	v_fmac_f32_e32 v107, v31, v221
	v_fmac_f32_e32 v104, v32, v222
	v_fmac_f32_e32 v105, v33, v223
	v_fmac_f32_e32 v100, v26, v224
	v_fmac_f32_e32 v101, v27, v225
	v_fmac_f32_e32 v102, v28, v226
	v_fmac_f32_e32 v103, v29, v227
	s_add_i32 s39, s39, 1
	v_lshl_add_u64 v[128:129], v[128:129], 0, s[18:19]
	v_lshl_add_u64 v[132:133], v[132:133], 0, s[18:19]
	s_cmp_eq_u32 s39, 3
	s_mov_b64 s[12:13], -1
	s_barrier
	s_cbranch_scc0 .LBB0_23
; __device__ __forceinline__ void phase_merge(const Params& p, u16* smem, volatile LAS unsigned* vb_) {
;     ...
; #pragma unroll
;     for (int i = 0; i < 4; ++i)
; #pragma unroll
;       for (int j = 0; j < 4; ++j)
; #pragma unroll
;         for (int r = 0; r < 4; ++r)
;           smem[(wm * 64 + i * 16 + (lane >> 4) * 4 + r) * 264 + wn * 64 + j * 16 + (lane & 15)] = f2bf(tot[i][j][r]);
;     __syncthreads();
	v_cvt_pk_bf16_f32 v0, v170, s0
	ds_write_b16 v94, v0
	v_cvt_pk_bf16_f32 v0, v171, s0
	ds_write_b16 v94, v0 offset:528
	v_cvt_pk_bf16_f32 v0, v168, s0
	ds_write_b16 v94, v0 offset:1056
	v_cvt_pk_bf16_f32 v0, v169, s0
	ds_write_b16 v94, v0 offset:1584
	v_cvt_pk_bf16_f32 v0, v166, s0
	ds_write_b16 v94, v0 offset:32
	v_cvt_pk_bf16_f32 v0, v167, s0
	ds_write_b16 v94, v0 offset:560
	v_cvt_pk_bf16_f32 v0, v164, s0
	ds_write_b16 v94, v0 offset:1088
	v_cvt_pk_bf16_f32 v0, v165, s0
	ds_write_b16 v94, v0 offset:1616
	v_cvt_pk_bf16_f32 v0, v162, s0
	ds_write_b16 v94, v0 offset:64
	v_cvt_pk_bf16_f32 v0, v163, s0
	ds_write_b16 v94, v0 offset:592
	v_cvt_pk_bf16_f32 v0, v160, s0
	ds_write_b16 v94, v0 offset:1120
	v_cvt_pk_bf16_f32 v0, v161, s0
	ds_write_b16 v94, v0 offset:1648
	v_cvt_pk_bf16_f32 v0, v158, s0
	ds_write_b16 v94, v0 offset:96
	v_cvt_pk_bf16_f32 v0, v159, s0
	ds_write_b16 v94, v0 offset:624
	v_cvt_pk_bf16_f32 v0, v156, s0
	ds_write_b16 v94, v0 offset:1152
	v_cvt_pk_bf16_f32 v0, v157, s0
	ds_write_b16 v94, v0 offset:1680
	v_cvt_pk_bf16_f32 v0, v154, s0
	ds_write_b16 v94, v0 offset:8448
	v_cvt_pk_bf16_f32 v0, v155, s0
	ds_write_b16 v94, v0 offset:8976
	v_cvt_pk_bf16_f32 v0, v152, s0
	ds_write_b16 v94, v0 offset:9504
	v_cvt_pk_bf16_f32 v0, v153, s0
	ds_write_b16 v94, v0 offset:10032
	v_cvt_pk_bf16_f32 v0, v150, s0
	ds_write_b16 v94, v0 offset:8480
	v_cvt_pk_bf16_f32 v0, v151, s0
	ds_write_b16 v94, v0 offset:9008
	v_cvt_pk_bf16_f32 v0, v148, s0
	ds_write_b16 v94, v0 offset:9536
	v_cvt_pk_bf16_f32 v0, v149, s0
	ds_write_b16 v94, v0 offset:10064
	v_cvt_pk_bf16_f32 v0, v146, s0
	ds_write_b16 v94, v0 offset:8512
	v_cvt_pk_bf16_f32 v0, v147, s0
	ds_write_b16 v94, v0 offset:9040
	v_cvt_pk_bf16_f32 v0, v144, s0
	ds_write_b16 v94, v0 offset:9568
	v_cvt_pk_bf16_f32 v0, v145, s0
	ds_write_b16 v94, v0 offset:10096
	v_cvt_pk_bf16_f32 v0, v138, s0
	ds_write_b16 v94, v0 offset:8544
	v_cvt_pk_bf16_f32 v0, v139, s0
	ds_write_b16 v94, v0 offset:9072
	v_cvt_pk_bf16_f32 v0, v136, s0
	ds_write_b16 v94, v0 offset:9600
	v_cvt_pk_bf16_f32 v0, v137, s0
	ds_write_b16 v94, v0 offset:10128
	v_cvt_pk_bf16_f32 v0, v134, s0
	ds_write_b16 v94, v0 offset:16896
	v_cvt_pk_bf16_f32 v0, v135, s0
	ds_write_b16 v94, v0 offset:17424
	v_cvt_pk_bf16_f32 v0, v130, s0
	ds_write_b16 v94, v0 offset:17952
	v_cvt_pk_bf16_f32 v0, v131, s0
	ds_write_b16 v94, v0 offset:18480
	v_cvt_pk_bf16_f32 v0, v126, s0
	ds_write_b16 v94, v0 offset:16928
	v_cvt_pk_bf16_f32 v0, v127, s0
	ds_write_b16 v94, v0 offset:17456
	v_cvt_pk_bf16_f32 v0, v124, s0
	ds_write_b16 v94, v0 offset:17984
	v_cvt_pk_bf16_f32 v0, v125, s0
	ds_write_b16 v94, v0 offset:18512
	v_cvt_pk_bf16_f32 v0, v122, s0
	ds_write_b16 v94, v0 offset:16960
	v_cvt_pk_bf16_f32 v0, v123, s0
	ds_write_b16 v94, v0 offset:17488
	v_cvt_pk_bf16_f32 v0, v120, s0
	ds_write_b16 v94, v0 offset:18016
	v_cvt_pk_bf16_f32 v0, v121, s0
	ds_write_b16 v94, v0 offset:18544
	v_cvt_pk_bf16_f32 v0, v118, s0
	ds_write_b16 v94, v0 offset:16992
	v_cvt_pk_bf16_f32 v0, v119, s0
	ds_write_b16 v94, v0 offset:17520
	v_cvt_pk_bf16_f32 v0, v116, s0
	ds_write_b16 v94, v0 offset:18048
	v_cvt_pk_bf16_f32 v0, v117, s0
	ds_write_b16 v94, v0 offset:18576
	v_cvt_pk_bf16_f32 v0, v114, s0
	ds_write_b16 v94, v0 offset:25344
	v_cvt_pk_bf16_f32 v0, v115, s0
	ds_write_b16 v94, v0 offset:25872
	v_cvt_pk_bf16_f32 v0, v112, s0
	ds_write_b16 v94, v0 offset:26400
	v_cvt_pk_bf16_f32 v0, v113, s0
	ds_write_b16 v94, v0 offset:26928
	v_cvt_pk_bf16_f32 v0, v110, s0
	ds_write_b16 v94, v0 offset:25376
	v_cvt_pk_bf16_f32 v0, v111, s0
	ds_write_b16 v94, v0 offset:25904
	v_cvt_pk_bf16_f32 v0, v108, s0
	ds_write_b16 v94, v0 offset:26432
	v_cvt_pk_bf16_f32 v0, v109, s0
	ds_write_b16 v94, v0 offset:26960
	v_cvt_pk_bf16_f32 v0, v106, s0
	ds_write_b16 v94, v0 offset:25408
	v_cvt_pk_bf16_f32 v0, v107, s0
	ds_write_b16 v94, v0 offset:25936
	v_cvt_pk_bf16_f32 v0, v104, s0
	ds_write_b16 v94, v0 offset:26464
	v_cvt_pk_bf16_f32 v0, v105, s0
	ds_write_b16 v94, v0 offset:26992
	v_cvt_pk_bf16_f32 v0, v100, s0
	ds_write_b16 v94, v0 offset:25440
	v_cvt_pk_bf16_f32 v0, v101, s0
	ds_write_b16 v94, v0 offset:25968
	v_cvt_pk_bf16_f32 v0, v102, s0
	ds_write_b16 v94, v0 offset:26496
	v_cvt_pk_bf16_f32 v0, v103, s0
	v_mov_b32_e32 v38, v175
	v_readlane_b32 s12, v252, 38
	ds_write_b16 v94, v0 offset:27024
	s_waitcnt lgkmcnt(0)
	s_barrier
; #define RTID opaque_tid()
; __device__ __forceinline__ void phase_merge(const Params& p, u16* smem, volatile LAS unsigned* vb_) {
;     ...
;     const int tid3 = RTID;
; #pragma unroll
;     for (int k = 0; k < 8; ++k) {
;       const int c = tid3 + 512 * k;
;       const int row = c >> 5, ch = c & 31;
;       *(uint4*)(outp + (size_t)(mt * 128 + row) * 1024 + nt * 256 + ch * 8) = *(const uint4*)(smem + row * 264 + ch * 8);
;     }
;     __syncthreads();
;   }
	v_readlane_b32 s13, v252, 39
	v_lshlrev_b32_e32 v0, 4, v38
	s_add_u32 s12, s12, s42
	v_and_b32_e32 v0, 0x1f0, v0
	s_addc_u32 s13, s13, s43
	v_ashrrev_i32_e32 v28, 5, v38
	v_lshl_add_u64 v[34:35], s[12:13], 0, v[0:1]
	v_mad_u64_u32 v[26:27], s[12:13], v28, s2, v[0:1]
	v_add_u32_e32 v28, s22, v28
	v_ashrrev_i32_e32 v29, 31, v28
	v_lshlrev_b64 v[28:29], 11, v[28:29]
	v_lshl_add_u64 v[36:37], v[34:35], 0, v[28:29]
	ds_read_b128 v[26:29], v26
	v_add_u32_e32 v30, 0x200, v38
	v_ashrrev_i32_e32 v39, 5, v30
	v_mad_u64_u32 v[30:31], s[12:13], v39, s2, v[0:1]
	ds_read_b128 v[30:33], v30
	s_waitcnt lgkmcnt(1)
	global_store_dwordx4 v[36:37], v[26:29], off
	s_add_i32 s10, s10, s70
	s_and_b64 vcc, exec, s[0:1]
	v_add_u32_e32 v26, s22, v39
	v_ashrrev_i32_e32 v27, 31, v26
	v_lshlrev_b64 v[26:27], 11, v[26:27]
	v_lshl_add_u64 v[26:27], v[34:35], 0, v[26:27]
	s_waitcnt lgkmcnt(0)
	global_store_dwordx4 v[26:27], v[30:33], off
	v_add_u32_e32 v26, 0x400, v38
	v_ashrrev_i32_e32 v28, 5, v26
	v_mad_u64_u32 v[26:27], s[12:13], v28, s2, v[0:1]
	v_add_u32_e32 v28, s22, v28
	v_ashrrev_i32_e32 v29, 31, v28
	v_lshlrev_b64 v[28:29], 11, v[28:29]
	v_lshl_add_u64 v[36:37], v[34:35], 0, v[28:29]
	ds_read_b128 v[26:29], v26
	v_add_u32_e32 v30, 0x600, v38
	v_ashrrev_i32_e32 v39, 5, v30
	v_mad_u64_u32 v[30:31], s[12:13], v39, s2, v[0:1]
	ds_read_b128 v[30:33], v30
	s_waitcnt lgkmcnt(1)
	global_store_dwordx4 v[36:37], v[26:29], off
	s_nop 1
	v_add_u32_e32 v26, s22, v39
	v_ashrrev_i32_e32 v27, 31, v26
	v_lshlrev_b64 v[26:27], 11, v[26:27]
	v_lshl_add_u64 v[26:27], v[34:35], 0, v[26:27]
	s_waitcnt lgkmcnt(0)
	global_store_dwordx4 v[26:27], v[30:33], off
	v_add_u32_e32 v26, 0x800, v38
	v_ashrrev_i32_e32 v28, 5, v26
	v_mad_u64_u32 v[26:27], s[12:13], v28, s2, v[0:1]
	v_add_u32_e32 v28, s22, v28
	v_ashrrev_i32_e32 v29, 31, v28
	v_lshlrev_b64 v[28:29], 11, v[28:29]
	v_lshl_add_u64 v[36:37], v[34:35], 0, v[28:29]
	ds_read_b128 v[26:29], v26
	v_add_u32_e32 v30, 0xa00, v38
	v_ashrrev_i32_e32 v39, 5, v30
	v_mad_u64_u32 v[30:31], s[12:13], v39, s2, v[0:1]
	ds_read_b128 v[30:33], v30
	s_waitcnt lgkmcnt(1)
	global_store_dwordx4 v[36:37], v[26:29], off
	s_nop 1
	v_add_u32_e32 v26, s22, v39
	v_ashrrev_i32_e32 v27, 31, v26
	v_lshlrev_b64 v[26:27], 11, v[26:27]
	v_lshl_add_u64 v[26:27], v[34:35], 0, v[26:27]
	s_waitcnt lgkmcnt(0)
	global_store_dwordx4 v[26:27], v[30:33], off
	v_add_u32_e32 v26, 0xc00, v38
	v_ashrrev_i32_e32 v28, 5, v26
	v_mad_u64_u32 v[26:27], s[12:13], v28, s2, v[0:1]
	v_add_u32_e32 v28, s22, v28
	v_ashrrev_i32_e32 v29, 31, v28
	v_lshlrev_b64 v[28:29], 11, v[28:29]
	v_lshl_add_u64 v[36:37], v[34:35], 0, v[28:29]
	ds_read_b128 v[26:29], v26
	v_add_u32_e32 v30, 0xe00, v38
	v_ashrrev_i32_e32 v38, 5, v30
	v_mad_u64_u32 v[30:31], s[12:13], v38, s2, v[0:1]
	ds_read_b128 v[30:33], v30
	s_waitcnt lgkmcnt(1)
	global_store_dwordx4 v[36:37], v[26:29], off
	v_readlane_b32 s12, v254, 30
	s_add_i32 s21, s21, s12
	v_add_u32_e32 v26, s22, v38
	v_ashrrev_i32_e32 v27, 31, v26
	v_lshlrev_b64 v[26:27], 11, v[26:27]
	v_lshl_add_u64 v[26:27], v[34:35], 0, v[26:27]
	s_mov_b64 s[12:13], -1
	s_waitcnt lgkmcnt(0)
	global_store_dwordx4 v[26:27], v[30:33], off
	s_barrier
	s_cbranch_vccz .LBB0_22
